# prologue grid.sync() replaced by a single-counter grid barrier (wbl2 + atomic arrive + sc1 poll + inv)
# speedup vs baseline: 1.0013x; 1.0013x over previous
; __device__ __forceinline__ void ln_panel(const float* src, float* dst, bf16_t* dstb, const float* gam, const float* bet, LAS f32x2* T) {
;     ...
;     for (int it = 0; it < 32 / NB; ++it) {
;         const int r = r0 + it * NB;
;         if (it + 1 < 32 / NB) {
; #pragma unroll
;             for (int b = 0; b < NB; ++b)
; #pragma unroll
;                 for (int j = 0; j < 4; ++j) nxt[b][j] = ((const f32x4*)(src + (size_t)(r + NB + b) * DM))[lane + 64 * j];
;         }
;         float s[NB], s2[NB];
; #pragma unroll
;         for (int b = 0; b < NB; ++b) { s[b] = 0.f;
; #pragma unroll
;             for (int j = 0; j < 4; ++j) s[b] += (cur[b][j].x + cur[b][j].y) + (cur[b][j].z + cur[b][j].w); }
; #pragma unroll
;         for (int o = 1; o < 64; o <<= 1)
; #pragma unroll
;             for (int b = 0; b < NB; ++b) s[b] += __shfl_xor(s[b], o);
; #pragma unroll
;         for (int b = 0; b < NB; ++b) { const float mean = s[b] * (1.f / DM); s2[b] = 0.f;
; #pragma unroll
;             for (int j = 0; j < 4; ++j) { cur[b][j] = cur[b][j] - mean; s2[b] += (cur[b][j].x * cur[b][j].x + cur[b][j].y * cur[b][j].y) + (cur[b][j].z * cur[b][j].z + cur[b][j].w * cur[b][j].w); } }
; #pragma unroll
;         for (int o = 1; o < 64; o <<= 1)
; #pragma unroll
;             for (int b = 0; b < NB; ++b) s2[b] += __shfl_xor(s2[b], o);
.LBB0_107:
	v_lshl_add_u64 v[66:67], v[102:103], 0, s[12:13]
	s_waitcnt vmcnt(15)
	v_mov_b32_e32 v68, v35
	v_mov_b32_e32 v69, v36
	v_mov_b32_e32 v70, v34
	v_mov_b32_e32 v71, v37
	s_waitcnt vmcnt(14)
	v_mov_b32_e32 v72, v39
	v_mov_b32_e32 v73, v40
	v_mov_b32_e32 v74, v38
	v_mov_b32_e32 v75, v41
	v_add_co_u32_e32 v110, vcc, 0x2000, v66
	s_waitcnt vmcnt(11)
	v_mov_b32_e32 v80, v51
	v_mov_b32_e32 v81, v52
	v_mov_b32_e32 v82, v50
	v_mov_b32_e32 v83, v53
	s_waitcnt vmcnt(10)
	v_mov_b32_e32 v84, v55
	v_mov_b32_e32 v85, v56
	v_mov_b32_e32 v86, v54
	v_mov_b32_e32 v87, v57
	v_pk_add_f32 v[68:69], v[68:69], v[70:71]
	v_pk_add_f32 v[70:71], v[72:73], v[74:75]
	v_addc_co_u32_e32 v111, vcc, 0, v67, vcc
	v_pk_add_f32 v[72:73], v[80:81], v[82:83]
	v_pk_add_f32 v[74:75], v[84:85], v[86:87]
	v_add_co_u32_e32 v116, vcc, 0x3000, v66
	v_add_f32_e32 v66, v68, v69
	v_pk_add_f32 v[118:119], v[70:71], v[70:71] op_sel:[0,1] op_sel_hi:[1,0]
	v_add_f32_e32 v76, v42, v43
	v_add_f32_e32 v78, v44, v45
	v_mov_b32_e32 v105, v46
	v_mov_b32_e32 v77, v48
	v_mov_b32_e32 v79, v49
	v_add_f32_e32 v68, v72, v73
	v_pk_add_f32 v[120:121], v[74:75], v[74:75] op_sel:[0,1] op_sel_hi:[1,0]
	v_add_f32_e32 v104, 0, v66
	v_mov_b32_e32 v119, v47
	s_waitcnt vmcnt(9)
	v_add_f32_e32 v88, v58, v59
	v_add_f32_e32 v90, v60, v61
	s_waitcnt vmcnt(8)
	v_mov_b32_e32 v107, v62
	v_mov_b32_e32 v89, v64
	v_mov_b32_e32 v91, v65
	v_pk_add_f32 v[112:113], v[76:77], v[78:79]
	v_add_f32_e32 v106, 0, v68
	v_mov_b32_e32 v121, v63
	v_pk_add_f32 v[104:105], v[104:105], v[118:119]
	v_pk_add_f32 v[114:115], v[88:89], v[90:91]
	v_pk_add_f32 v[106:107], v[106:107], v[120:121]
	v_pk_add_f32 v[104:105], v[104:105], v[112:113]
	v_pk_add_f32 v[106:107], v[106:107], v[114:115]
	v_add_f32_e32 v104, v104, v105
	v_add_f32_e32 v105, v106, v107
	ds_bpermute_b32 v106, v191, v104
	ds_bpermute_b32 v107, v191, v105
	v_addc_co_u32_e32 v117, vcc, 0, v67, vcc
	global_load_dwordx4 v[94:97], v[110:111], off
	global_load_dwordx4 v[90:93], v[110:111], off offset:1024
	global_load_dwordx4 v[86:89], v[110:111], off offset:2048
	global_load_dwordx4 v[82:85], v[110:111], off offset:3072
	s_waitcnt lgkmcnt(1)
	v_add_f32_e32 v104, v104, v106
	s_waitcnt lgkmcnt(0)
	v_add_f32_e32 v105, v105, v107
	ds_bpermute_b32 v106, v218, v104
	ds_bpermute_b32 v107, v218, v105
	global_load_dwordx4 v[78:81], v[116:117], off
	global_load_dwordx4 v[74:77], v[116:117], off offset:1024
	global_load_dwordx4 v[70:73], v[116:117], off offset:2048
	global_load_dwordx4 v[66:69], v[116:117], off offset:3072
	s_add_u32 s12, s12, 0x2000
	s_addc_u32 s13, s13, 0
	s_waitcnt lgkmcnt(1)
	v_add_f32_e32 v104, v104, v106
	s_waitcnt lgkmcnt(0)
	v_add_f32_e32 v105, v105, v107
	ds_bpermute_b32 v106, v219, v104
	ds_bpermute_b32 v107, v219, v105
	s_cmp_eq_u32 s12, 0x1e000
	s_waitcnt lgkmcnt(1)
	v_add_f32_e32 v104, v104, v106
	s_waitcnt lgkmcnt(0)
	v_add_f32_e32 v105, v105, v107
	ds_bpermute_b32 v106, v220, v104
	ds_bpermute_b32 v107, v220, v105
	s_waitcnt lgkmcnt(1)
	v_add_f32_e32 v104, v104, v106
	s_waitcnt lgkmcnt(0)
	v_add_f32_e32 v105, v105, v107
	ds_bpermute_b32 v106, v221, v104
	ds_bpermute_b32 v107, v221, v105
	s_waitcnt lgkmcnt(1)
	v_add_f32_e32 v104, v104, v106
	s_waitcnt lgkmcnt(0)
	v_add_f32_e32 v105, v105, v107
	ds_bpermute_b32 v106, v222, v104
	ds_bpermute_b32 v107, v222, v105
	s_waitcnt lgkmcnt(1)
	v_add_f32_e32 v104, v104, v106
	s_waitcnt lgkmcnt(0)
	v_add_f32_e32 v105, v105, v107
	v_fmamk_f32 v35, v104, 0xba800000, v35
	v_fmamk_f32 v34, v104, 0xba800000, v34
	v_fmamk_f32 v37, v104, 0xba800000, v37
	v_fmac_f32_e32 v36, 0xba800000, v104
	v_fmamk_f32 v39, v104, 0xba800000, v39
	v_fmamk_f32 v38, v104, 0xba800000, v38
	v_fmamk_f32 v41, v104, 0xba800000, v41
	v_fmac_f32_e32 v40, 0xba800000, v104
	v_fmamk_f32 v43, v104, 0xba800000, v43
	v_fmamk_f32 v42, v104, 0xba800000, v42
	v_fmamk_f32 v45, v104, 0xba800000, v45
	v_fmac_f32_e32 v44, 0xba800000, v104
	v_fmamk_f32 v49, v104, 0xba800000, v49
	v_fmamk_f32 v48, v104, 0xba800000, v48
	v_fmamk_f32 v47, v104, 0xba800000, v47
	v_fmac_f32_e32 v46, 0xba800000, v104
	v_fmamk_f32 v51, v105, 0xba800000, v51
	v_fmamk_f32 v50, v105, 0xba800000, v50
	v_fmamk_f32 v53, v105, 0xba800000, v53
	v_fmac_f32_e32 v52, 0xba800000, v105
	v_fmamk_f32 v55, v105, 0xba800000, v55
	v_fmamk_f32 v54, v105, 0xba800000, v54
	v_fmamk_f32 v57, v105, 0xba800000, v57
	v_fmac_f32_e32 v56, 0xba800000, v105
	v_fmamk_f32 v59, v105, 0xba800000, v59
	v_fmamk_f32 v58, v105, 0xba800000, v58
	v_fmamk_f32 v61, v105, 0xba800000, v61
	v_fmac_f32_e32 v60, 0xba800000, v105
	v_fmamk_f32 v65, v105, 0xba800000, v65
	v_fmamk_f32 v64, v105, 0xba800000, v64
	v_fmamk_f32 v63, v105, 0xba800000, v63
	v_fmac_f32_e32 v62, 0xba800000, v105
	v_pk_mul_f32 v[104:105], v[36:37], v[36:37]
	v_pk_mul_f32 v[106:107], v[34:35], v[34:35]
	v_pk_mul_f32 v[110:111], v[40:41], v[40:41]
	v_pk_mul_f32 v[112:113], v[38:39], v[38:39]
	v_mul_f32_e32 v114, v42, v42
	v_mul_f32_e32 v116, v44, v44
	v_pk_mul_f32 v[118:119], v[52:53], v[52:53]
	v_pk_mul_f32 v[120:121], v[50:51], v[50:51]
	v_pk_mul_f32 v[122:123], v[56:57], v[56:57]
	v_pk_mul_f32 v[124:125], v[54:55], v[54:55]
	v_pk_mov_b32 v[130:131], v[106:107], v[104:105] op_sel:[1,0]
	v_mov_b32_e32 v107, v105
	v_pk_mov_b32 v[104:105], v[112:113], v[110:111] op_sel:[1,0]
	v_mov_b32_e32 v113, v111
	v_pk_fma_f32 v[110:111], v[42:43], v[42:43], v[114:115] op_sel_hi:[1,1,0]
	v_pk_fma_f32 v[114:115], v[44:45], v[44:45], v[116:117] op_sel_hi:[1,1,0]
	v_pk_mov_b32 v[116:117], v[120:121], v[118:119] op_sel:[1,0]
	v_mov_b32_e32 v121, v119
	v_pk_mov_b32 v[118:119], v[124:125], v[122:123] op_sel:[1,0]
	v_mov_b32_e32 v125, v123
	v_pk_add_f32 v[106:107], v[130:131], v[106:107]
	v_pk_add_f32 v[104:105], v[104:105], v[112:113]
	v_mul_f32_e32 v126, v58, v58
	v_mul_f32_e32 v128, v60, v60
	v_mul_f32_e32 v110, v46, v46
	v_mul_f32_e32 v114, v47, v47
	v_pk_add_f32 v[112:113], v[116:117], v[120:121]
	v_pk_add_f32 v[116:117], v[118:119], v[124:125]
	v_pk_add_f32 v[106:107], v[106:107], v[106:107] op_sel_hi:[0,1]
	v_pk_add_f32 v[104:105], v[104:105], v[104:105] op_sel_hi:[0,1]
	v_pk_fma_f32 v[122:123], v[58:59], v[58:59], v[126:127] op_sel_hi:[1,1,0]
	v_pk_fma_f32 v[126:127], v[60:61], v[60:61], v[128:129] op_sel_hi:[1,1,0]
	v_pk_add_f32 v[110:111], v[110:111], v[114:115]
	v_pk_add_f32 v[112:113], v[112:113], v[112:113] op_sel_hi:[0,1]
	v_pk_add_f32 v[114:115], v[116:117], v[116:117] op_sel_hi:[0,1]
	v_mul_f32_e32 v106, v48, v48
	v_mul_f32_e32 v104, v49, v49
	v_mul_f32_e32 v122, v62, v62
	v_mul_f32_e32 v126, v63, v63
	v_mul_f32_e32 v112, v64, v64
	v_mul_f32_e32 v114, v65, v65
	v_pk_add_f32 v[104:105], v[106:107], v[104:105]
	v_pk_add_f32 v[116:117], v[122:123], v[126:127]
	v_pk_add_f32 v[106:107], v[112:113], v[114:115]
	v_pk_add_f32 v[104:105], v[110:111], v[104:105]
	v_pk_add_f32 v[106:107], v[116:117], v[106:107]
	v_add_f32_e32 v104, v104, v105
	v_add_f32_e32 v105, v106, v107
	ds_bpermute_b32 v106, v191, v104
	ds_bpermute_b32 v107, v191, v105
	s_waitcnt lgkmcnt(1)
; __device__ __forceinline__ unsigned pk2(float lo, float hi) { unsigned r; asm("v_cvt_pk_bf16_f32 %0, %1, %2" : "=v"(r) : "v"(lo), "v"(hi)); return r; }
; __device__ __forceinline__ void ln_panel(const float* src, float* dst, bf16_t* dstb, const float* gam, const float* bet, LAS f32x2* T) {
;     ...
; #pragma unroll
;         for (int b = 0; b < NB; ++b) {
;             const float rstd = 1.f / sqrtf(s2[b] * (1.f / DM) + LN_EPS);
;             if (T && lane == 0) T[r + b] = (f32x2){s[b] * (1.f / DM), rstd};
; #pragma unroll
;             for (int j = 0; j < 4; ++j) {
;                 const f32x4 o = cur[b][j] * rstd * gv[j] + bv[j];
;                 if (dst) ((f32x4*)(dst + (size_t)(r + b) * DM))[lane + 64 * j] = o;
;                 if (dstb) { u32x2 w; w.x = pk2(o.x, o.y); w.y = pk2(o.z, o.w); ((u32x2*)(dstb + (size_t)(r + b) * DM))[lane + 64 * j] = w; }
;             }
;         }
; #pragma unroll
;         for (int b = 0; b < NB; ++b)
; #pragma unroll
;             for (int j = 0; j < 4; ++j) cur[b][j] = nxt[b][j];
;     }
	v_add_f32_e32 v104, v104, v106
	s_waitcnt lgkmcnt(0)
	v_add_f32_e32 v105, v105, v107
	ds_bpermute_b32 v106, v218, v104
	ds_bpermute_b32 v107, v218, v105
	s_waitcnt lgkmcnt(1)
	v_add_f32_e32 v104, v104, v106
	s_waitcnt lgkmcnt(0)
	v_add_f32_e32 v105, v105, v107
	ds_bpermute_b32 v106, v219, v104
	ds_bpermute_b32 v107, v219, v105
	s_waitcnt lgkmcnt(1)
	v_add_f32_e32 v104, v104, v106
	s_waitcnt lgkmcnt(0)
	v_add_f32_e32 v105, v105, v107
	ds_bpermute_b32 v106, v220, v104
	ds_bpermute_b32 v107, v220, v105
	s_waitcnt lgkmcnt(1)
	v_add_f32_e32 v104, v104, v106
	s_waitcnt lgkmcnt(0)
	v_add_f32_e32 v105, v105, v107
	ds_bpermute_b32 v106, v221, v104
	ds_bpermute_b32 v107, v221, v105
	s_waitcnt lgkmcnt(1)
	v_add_f32_e32 v104, v104, v106
	s_waitcnt lgkmcnt(0)
	v_add_f32_e32 v105, v105, v107
	ds_bpermute_b32 v106, v222, v104
	ds_bpermute_b32 v107, v222, v105
	s_waitcnt lgkmcnt(1)
	v_add_f32_e32 v104, v104, v106
	s_waitcnt lgkmcnt(0)
	v_add_f32_e32 v105, v105, v107
	v_fmamk_f32 v104, v104, 0x3a800000, v99
	v_fmamk_f32 v105, v105, 0x3a800000, v99
	v_mul_f32_e32 v106, 0x4f800000, v104
	v_cmp_gt_f32_e64 s[4:5], s11, v104
	v_mul_f32_e32 v107, 0x4f800000, v105
	v_cmp_gt_f32_e32 vcc, s11, v105
	v_cndmask_b32_e64 v104, v104, v106, s[4:5]
	v_sqrt_f32_e32 v106, v104
	v_cndmask_b32_e32 v105, v105, v107, vcc
	v_sqrt_f32_e32 v107, v105
	v_add_u32_e32 v109, -1, v106
	v_add_u32_e32 v110, 1, v106
	v_add_u32_e32 v111, -1, v107
	v_fma_f32 v113, -v109, v106, v104
	v_add_u32_e32 v112, 1, v107
	v_fma_f32 v114, -v110, v106, v104
	v_fma_f32 v115, -v111, v107, v105
	v_cmp_ge_f32_e64 s[6:7], 0, v113
	v_fma_f32 v116, -v112, v107, v105
	v_cmp_lt_f32_e64 s[8:9], 0, v114
	v_cndmask_b32_e64 v106, v106, v109, s[6:7]
	v_cmp_ge_f32_e64 s[6:7], 0, v115
	v_cndmask_b32_e64 v106, v106, v110, s[8:9]
	v_mul_f32_e32 v109, 0x37800000, v106
	v_cndmask_b32_e64 v107, v107, v111, s[6:7]
	v_cmp_lt_f32_e64 s[6:7], 0, v116
	v_cndmask_b32_e64 v106, v106, v109, s[4:5]
	v_cmp_class_f32_e64 s[4:5], v104, v108
	v_cndmask_b32_e64 v107, v107, v112, s[6:7]
	v_mul_f32_e32 v110, 0x37800000, v107
	v_cndmask_b32_e32 v107, v107, v110, vcc
	v_cmp_class_f32_e32 vcc, v105, v108
	v_cndmask_b32_e64 v104, v106, v104, s[4:5]
	s_nop 0
	v_cndmask_b32_e32 v109, v107, v105, vcc
	v_div_scale_f32 v105, s[4:5], v104, v104, 1.0
	v_rcp_f32_e32 v111, v105
	v_div_scale_f32 v107, s[4:5], v109, v109, 1.0
	v_rcp_f32_e32 v112, v107
	v_fma_f32 v113, -v105, v111, 1.0
	v_div_scale_f32 v106, vcc, 1.0, v104, 1.0
	v_fmac_f32_e32 v111, v113, v111
	v_fma_f32 v114, -v107, v112, 1.0
	v_mul_f32_e32 v113, v106, v111
	v_div_scale_f32 v110, s[4:5], 1.0, v109, 1.0
	v_fmac_f32_e32 v112, v114, v112
	v_fma_f32 v115, -v105, v113, v106
	v_mul_f32_e32 v114, v110, v112
	v_fmac_f32_e32 v113, v115, v111
	v_fma_f32 v116, -v107, v114, v110
	v_fma_f32 v105, -v105, v113, v106
	v_fmac_f32_e32 v114, v116, v112
	v_div_fmas_f32 v105, v105, v111, v113
	v_fma_f32 v106, -v107, v114, v110
	v_div_fixup_f32 v104, v105, v104, 1.0
	s_mov_b64 vcc, s[4:5]
	v_div_fmas_f32 v122, v106, v112, v114
	v_pk_mul_f32 v[106:107], v[34:35], v[104:105] op_sel_hi:[1,0]
	v_pk_mul_f32 v[110:111], v[36:37], v[104:105] op_sel_hi:[1,0]
	v_pk_mul_f32 v[112:113], v[38:39], v[104:105] op_sel_hi:[1,0]
	v_pk_mul_f32 v[114:115], v[40:41], v[104:105] op_sel_hi:[1,0]
	v_pk_mul_f32 v[116:117], v[42:43], v[104:105] op_sel_hi:[1,0]
	v_pk_mul_f32 v[118:119], v[44:45], v[104:105] op_sel_hi:[1,0]
	v_pk_mul_f32 v[120:121], v[46:47], v[104:105] op_sel_hi:[1,0]
	v_pk_mul_f32 v[104:105], v[48:49], v[104:105] op_sel_hi:[1,0]
	v_div_fixup_f32 v122, v122, v109, 1.0
	s_waitcnt vmcnt(13)
	v_pk_fma_f32 v[106:107], v[26:27], v[106:107], v[30:31]
	v_pk_fma_f32 v[110:111], v[28:29], v[110:111], v[32:33]
	s_waitcnt vmcnt(12)
	v_pk_fma_f32 v[114:115], v[20:21], v[114:115], v[24:25]
	v_pk_fma_f32 v[112:113], v[18:19], v[112:113], v[22:23]
	s_waitcnt vmcnt(9)
	v_pk_fma_f32 v[116:117], v[10:11], v[116:117], v[14:15]
	s_waitcnt vmcnt(8)
	v_pk_fma_f32 v[104:105], v[4:5], v[104:105], v[8:9]
	v_pk_mul_f32 v[124:125], v[50:51], v[122:123] op_sel_hi:[1,0]
	v_pk_mul_f32 v[126:127], v[52:53], v[122:123] op_sel_hi:[1,0]
	v_cvt_pk_bf16_f32 v106, v106, v107
	v_cvt_pk_bf16_f32 v107, v110, v111
	s_waitcnt vmcnt(7)
	v_mov_b64_e32 v[34:35], v[94:95]
	s_waitcnt vmcnt(6)
	v_mov_b64_e32 v[38:39], v[90:91]
	s_waitcnt vmcnt(5)
	v_mov_b64_e32 v[42:43], v[86:87]
	s_waitcnt vmcnt(4)
	v_mov_b64_e32 v[46:47], v[82:83]
	v_pk_fma_f32 v[118:119], v[12:13], v[118:119], v[16:17]
	v_pk_fma_f32 v[120:121], v[2:3], v[120:121], v[6:7]
	v_pk_mul_f32 v[128:129], v[54:55], v[122:123] op_sel_hi:[1,0]
	v_pk_mul_f32 v[130:131], v[56:57], v[122:123] op_sel_hi:[1,0]
	v_pk_mul_f32 v[132:133], v[58:59], v[122:123] op_sel_hi:[1,0]
	v_pk_mul_f32 v[134:135], v[60:61], v[122:123] op_sel_hi:[1,0]
	v_pk_mul_f32 v[136:137], v[62:63], v[122:123] op_sel_hi:[1,0]
	v_pk_mul_f32 v[122:123], v[64:65], v[122:123] op_sel_hi:[1,0]
	s_waitcnt vmcnt(3)
	v_mov_b64_e32 v[50:51], v[78:79]
	s_waitcnt vmcnt(2)
	v_mov_b64_e32 v[54:55], v[74:75]
	s_waitcnt vmcnt(1)
	v_mov_b64_e32 v[58:59], v[70:71]
	s_waitcnt vmcnt(0)
	v_mov_b64_e32 v[62:63], v[66:67]
	v_cvt_pk_bf16_f32 v110, v112, v113
	v_cvt_pk_bf16_f32 v111, v114, v115
	v_cvt_pk_bf16_f32 v112, v116, v117
	v_cvt_pk_bf16_f32 v113, v118, v119
	v_cvt_pk_bf16_f32 v114, v120, v121
	v_cvt_pk_bf16_f32 v115, v104, v105
	v_pk_fma_f32 v[104:105], v[28:29], v[126:127], v[32:33]
	v_pk_fma_f32 v[116:117], v[26:27], v[124:125], v[30:31]
	global_store_dwordx2 v[100:101], v[106:107], off offset:-2048
	global_store_dwordx2 v[100:101], v[110:111], off offset:-1536
	global_store_dwordx2 v[100:101], v[112:113], off offset:-1024
	global_store_dwordx2 v[100:101], v[114:115], off offset:-512
	v_cvt_pk_bf16_f32 v106, v116, v117
	v_cvt_pk_bf16_f32 v107, v104, v105
	v_mov_b64_e32 v[36:37], v[96:97]
	v_mov_b64_e32 v[40:41], v[92:93]
	v_mov_b64_e32 v[44:45], v[88:89]
	v_mov_b64_e32 v[48:49], v[84:85]
	v_mov_b64_e32 v[52:53], v[80:81]
	v_mov_b64_e32 v[56:57], v[76:77]
	v_mov_b64_e32 v[60:61], v[72:73]
	v_mov_b64_e32 v[64:65], v[68:69]
	v_pk_fma_f32 v[118:119], v[20:21], v[130:131], v[24:25]
	v_pk_fma_f32 v[120:121], v[18:19], v[128:129], v[22:23]
	v_pk_fma_f32 v[124:125], v[12:13], v[134:135], v[16:17]
	v_pk_fma_f32 v[126:127], v[10:11], v[132:133], v[14:15]
	v_pk_fma_f32 v[122:123], v[4:5], v[122:123], v[8:9]
	v_pk_fma_f32 v[128:129], v[2:3], v[136:137], v[6:7]
	v_cvt_pk_bf16_f32 v104, v120, v121
	v_cvt_pk_bf16_f32 v105, v118, v119
	v_cvt_pk_bf16_f32 v110, v126, v127
	v_cvt_pk_bf16_f32 v111, v124, v125
	v_cvt_pk_bf16_f32 v113, v122, v123
	s_nop 0
	v_cvt_pk_bf16_f32 v112, v128, v129
	global_store_dwordx2 v[100:101], v[106:107], off
	global_store_dwordx2 v[100:101], v[104:105], off offset:512
	global_store_dwordx2 v[100:101], v[110:111], off offset:1024
	global_store_dwordx2 v[100:101], v[112:113], off offset:1536
	v_lshl_add_u64 v[100:101], v[100:101], 0, s[14:15]
	s_cbranch_scc0 .LBB0_107
; __device__ __forceinline__ void ln_panel(const float* src, float* dst, bf16_t* dstb, const float* gam, const float* bet, LAS f32x2* T) {
;     ...
;         float s[NB], s2[NB];
; #pragma unroll
;         for (int b = 0; b < NB; ++b) { s[b] = 0.f;
; #pragma unroll
;             for (int j = 0; j < 4; ++j) s[b] += (cur[b][j].x + cur[b][j].y) + (cur[b][j].z + cur[b][j].w); }
; #pragma unroll
;         for (int o = 1; o < 64; o <<= 1)
; #pragma unroll
;             for (int b = 0; b < NB; ++b) s[b] += __shfl_xor(s[b], o);
; #pragma unroll
;         for (int b = 0; b < NB; ++b) { const float mean = s[b] * (1.f / DM); s2[b] = 0.f;
; #pragma unroll
;             for (int j = 0; j < 4; ++j) { cur[b][j] = cur[b][j] - mean; s2[b] += (cur[b][j].x * cur[b][j].x + cur[b][j].y * cur[b][j].y) + (cur[b][j].z * cur[b][j].z + cur[b][j].w * cur[b][j].w); } }
; #pragma unroll
;         for (int o = 1; o < 64; o <<= 1)
; #pragma unroll
;             for (int b = 0; b < NB; ++b) s2[b] += __shfl_xor(s2[b], o);
	v_mov_b32_e32 v34, v95
	v_mov_b32_e32 v35, v96
	v_mov_b32_e32 v36, v94
	v_mov_b32_e32 v37, v97
	v_pk_add_f32 v[34:35], v[34:35], v[36:37]
	v_mov_b32_e32 v36, v91
	v_mov_b32_e32 v37, v92
	v_mov_b32_e32 v38, v90
	v_mov_b32_e32 v39, v93
	v_pk_add_f32 v[36:37], v[36:37], v[38:39]
	v_add_f32_e32 v34, v34, v35
	v_pk_add_f32 v[36:37], v[36:37], v[36:37] op_sel:[0,1] op_sel_hi:[1,0]
	v_add_f32_e32 v34, 0, v34
	v_add_f32_e32 v38, v86, v87
	v_add_f32_e32 v40, v88, v89
	v_mov_b32_e32 v35, v82
	v_mov_b32_e32 v37, v83
	v_mov_b32_e32 v39, v84
	v_mov_b32_e32 v41, v85
	v_pk_add_f32 v[34:35], v[34:35], v[36:37]
	v_pk_add_f32 v[36:37], v[38:39], v[40:41]
	v_mov_b32_e32 v38, v74
	v_pk_add_f32 v[34:35], v[34:35], v[36:37]
	v_mov_b32_e32 v36, v78
	v_add_f32_e32 v42, v34, v35
	v_mov_b32_e32 v34, v79
	v_mov_b32_e32 v35, v80
	v_mov_b32_e32 v37, v81
	v_pk_add_f32 v[34:35], v[34:35], v[36:37]
	v_mov_b32_e32 v36, v75
	v_mov_b32_e32 v37, v76
	v_mov_b32_e32 v39, v77
	v_pk_add_f32 v[36:37], v[36:37], v[38:39]
	v_add_f32_e32 v34, v34, v35
	v_pk_add_f32 v[36:37], v[36:37], v[36:37] op_sel:[0,1] op_sel_hi:[1,0]
	v_add_f32_e32 v34, 0, v34
	v_add_f32_e32 v38, v70, v71
	v_add_f32_e32 v40, v72, v73
	v_mov_b32_e32 v35, v66
	v_mov_b32_e32 v37, v67
	v_mov_b32_e32 v39, v68
	v_mov_b32_e32 v41, v69
	v_pk_add_f32 v[34:35], v[34:35], v[36:37]
	v_pk_add_f32 v[36:37], v[38:39], v[40:41]
	s_mov_b32 s11, 0xf800000
	v_pk_add_f32 v[34:35], v[34:35], v[36:37]
	v_readlane_b32 s4, v249, 4
	v_add_f32_e32 v34, v34, v35
	ds_bpermute_b32 v35, v191, v42
	ds_bpermute_b32 v36, v191, v34
	v_readlane_b32 s5, v249, 5
	s_lshl_b64 s[6:7], s[4:5], 1
	s_add_u32 s4, s24, s6
	s_waitcnt lgkmcnt(1)
	v_add_f32_e32 v35, v42, v35
	s_waitcnt lgkmcnt(0)
	v_add_f32_e32 v34, v34, v36
	ds_bpermute_b32 v36, v218, v35
	ds_bpermute_b32 v37, v218, v34
	v_writelane_b32 v249, s6, 8
	s_addc_u32 s5, s25, s7
	s_add_u32 s8, s4, 0x6000000
	s_waitcnt lgkmcnt(1)
	v_add_f32_e32 v35, v35, v36
	ds_bpermute_b32 v36, v219, v35
	s_waitcnt lgkmcnt(1)
	v_add_f32_e32 v34, v34, v37
	ds_bpermute_b32 v37, v219, v34
	s_addc_u32 s9, s5, 0
	v_writelane_b32 v249, s7, 9
	s_waitcnt lgkmcnt(1)
	v_add_f32_e32 v35, v35, v36
	ds_bpermute_b32 v36, v220, v35
	s_waitcnt lgkmcnt(1)
	v_add_f32_e32 v34, v34, v37
	ds_bpermute_b32 v37, v220, v34
	s_or_b32 s6, s10, 30
	s_ashr_i32 s7, s6, 31
	s_waitcnt lgkmcnt(1)
	v_add_f32_e32 v35, v35, v36
	ds_bpermute_b32 v36, v221, v35
	s_waitcnt lgkmcnt(1)
	v_add_f32_e32 v34, v34, v37
	ds_bpermute_b32 v37, v221, v34
	s_waitcnt lgkmcnt(1)
	v_add_f32_e32 v35, v35, v36
	ds_bpermute_b32 v36, v222, v35
	s_waitcnt lgkmcnt(1)
	v_add_f32_e32 v34, v34, v37
	ds_bpermute_b32 v37, v222, v34
	s_waitcnt lgkmcnt(1)
	v_add_f32_e32 v50, v35, v36
	v_fmamk_f32 v43, v50, 0xba800000, v95
	v_fmamk_f32 v42, v50, 0xba800000, v94
	v_fmamk_f32 v97, v50, 0xba800000, v97
	v_fmac_f32_e32 v96, 0xba800000, v50
	s_waitcnt lgkmcnt(0)
	v_add_f32_e32 v58, v34, v37
	v_pk_mul_f32 v[34:35], v[96:97], v[96:97]
	v_pk_mul_f32 v[36:37], v[42:43], v[42:43]
	v_fmamk_f32 v45, v50, 0xba800000, v91
	v_pk_mov_b32 v[38:39], v[36:37], v[34:35] op_sel:[1,0]
	v_mov_b32_e32 v37, v35
	v_pk_add_f32 v[34:35], v[38:39], v[36:37]
	v_fmamk_f32 v44, v50, 0xba800000, v90
	v_fmamk_f32 v93, v50, 0xba800000, v93
	v_fmac_f32_e32 v92, 0xba800000, v50
	v_pk_add_f32 v[34:35], v[34:35], v[34:35] op_sel_hi:[0,1]
	v_pk_mul_f32 v[36:37], v[92:93], v[92:93]
	v_pk_mul_f32 v[38:39], v[44:45], v[44:45]
	v_fmamk_f32 v46, v50, 0xba800000, v86
	v_pk_mov_b32 v[40:41], v[38:39], v[36:37] op_sel:[1,0]
	v_mov_b32_e32 v39, v37
	v_fmamk_f32 v47, v50, 0xba800000, v87
	v_fmac_f32_e32 v88, 0xba800000, v50
	v_mul_f32_e32 v34, v46, v46
	v_pk_add_f32 v[36:37], v[40:41], v[38:39]
	v_fmamk_f32 v89, v50, 0xba800000, v89
	v_pk_fma_f32 v[38:39], v[46:47], v[46:47], v[34:35] op_sel_hi:[1,1,0]
	v_mul_f32_e32 v34, v88, v88
	v_pk_add_f32 v[36:37], v[36:37], v[36:37] op_sel_hi:[0,1]
	v_pk_fma_f32 v[40:41], v[88:89], v[88:89], v[34:35] op_sel_hi:[1,1,0]
	v_fmamk_f32 v49, v50, 0xba800000, v85
	v_fmamk_f32 v48, v50, 0xba800000, v84
	v_fmamk_f32 v83, v50, 0xba800000, v83
	v_fmac_f32_e32 v82, 0xba800000, v50
	v_mul_f32_e32 v38, v82, v82
	v_mul_f32_e32 v40, v83, v83
	v_mul_f32_e32 v34, v48, v48
	v_mul_f32_e32 v36, v49, v49
	v_pk_add_f32 v[38:39], v[38:39], v[40:41]
	v_pk_add_f32 v[34:35], v[34:35], v[36:37]
	v_fmamk_f32 v81, v58, 0xba800000, v81
	v_pk_add_f32 v[34:35], v[38:39], v[34:35]
	v_fmac_f32_e32 v80, 0xba800000, v58
	v_add_f32_e32 v59, v34, v35
	v_fmamk_f32 v35, v58, 0xba800000, v79
	v_fmamk_f32 v34, v58, 0xba800000, v78
	v_pk_mul_f32 v[36:37], v[80:81], v[80:81]
	v_pk_mul_f32 v[38:39], v[34:35], v[34:35]
	v_fmamk_f32 v77, v58, 0xba800000, v77
	v_pk_mov_b32 v[40:41], v[38:39], v[36:37] op_sel:[1,0]
	v_mov_b32_e32 v39, v37
	v_pk_add_f32 v[36:37], v[40:41], v[38:39]
	v_fmamk_f32 v39, v58, 0xba800000, v75
	v_fmamk_f32 v38, v58, 0xba800000, v74
	v_fmac_f32_e32 v76, 0xba800000, v58
	v_pk_add_f32 v[50:51], v[36:37], v[36:37] op_sel_hi:[0,1]
	v_pk_mul_f32 v[36:37], v[76:77], v[76:77]
	v_pk_mul_f32 v[40:41], v[38:39], v[38:39]
	v_fmac_f32_e32 v72, 0xba800000, v58
	v_pk_mov_b32 v[52:53], v[40:41], v[36:37] op_sel:[1,0]
	v_mov_b32_e32 v41, v37
	v_pk_add_f32 v[36:37], v[52:53], v[40:41]
	v_fmamk_f32 v40, v58, 0xba800000, v70
	v_pk_add_f32 v[52:53], v[36:37], v[36:37] op_sel_hi:[0,1]
	v_fmamk_f32 v41, v58, 0xba800000, v71
	v_mul_f32_e32 v36, v40, v40
	v_fmamk_f32 v73, v58, 0xba800000, v73
	v_pk_fma_f32 v[54:55], v[40:41], v[40:41], v[36:37] op_sel_hi:[1,1,0]
	v_mul_f32_e32 v36, v72, v72
	v_pk_fma_f32 v[56:57], v[72:73], v[72:73], v[36:37] op_sel_hi:[1,1,0]
	v_fmamk_f32 v37, v58, 0xba800000, v69
	v_fmamk_f32 v36, v58, 0xba800000, v68
	v_fmamk_f32 v67, v58, 0xba800000, v67
	v_fmac_f32_e32 v66, 0xba800000, v58
	ds_bpermute_b32 v58, v191, v59
	v_mul_f32_e32 v54, v66, v66
	v_mul_f32_e32 v56, v67, v67
	v_mul_f32_e32 v50, v36, v36
	v_mul_f32_e32 v52, v37, v37
	v_pk_add_f32 v[54:55], v[54:55], v[56:57]
	v_pk_add_f32 v[50:51], v[50:51], v[52:53]
	s_nop 0
	v_pk_add_f32 v[50:51], v[54:55], v[50:51]
	s_nop 0
	v_add_f32_e32 v50, v50, v51
	s_waitcnt lgkmcnt(0)
; __device__ __forceinline__ unsigned pk2(float lo, float hi) { unsigned r; asm("v_cvt_pk_bf16_f32 %0, %1, %2" : "=v"(r) : "v"(lo), "v"(hi)); return r; }
; __device__ __forceinline__ void ln_panel(const float* src, float* dst, bf16_t* dstb, const float* gam, const float* bet, LAS f32x2* T) {
;     ...
;         for (int b = 0; b < NB; ++b) {
;             const float rstd = 1.f / sqrtf(s2[b] * (1.f / DM) + LN_EPS);
;             if (T && lane == 0) T[r + b] = (f32x2){s[b] * (1.f / DM), rstd};
; #pragma unroll
;             for (int j = 0; j < 4; ++j) {
;                 const f32x4 o = cur[b][j] * rstd * gv[j] + bv[j];
;                 if (dst) ((f32x4*)(dst + (size_t)(r + b) * DM))[lane + 64 * j] = o;
;                 if (dstb) { u32x2 w; w.x = pk2(o.x, o.y); w.y = pk2(o.z, o.w); ((u32x2*)(dstb + (size_t)(r + b) * DM))[lane + 64 * j] = w; }
;             }
;         }
; __global__ void __launch_bounds__(512, 2) fwd_megakernel(Args a) {
;     ...
;     grid.sync();
	v_add_f32_e32 v51, v59, v58
	ds_bpermute_b32 v52, v191, v50
	ds_bpermute_b32 v53, v218, v51
	s_waitcnt lgkmcnt(1)
	v_add_f32_e32 v50, v50, v52
	s_waitcnt lgkmcnt(0)
	v_add_f32_e32 v51, v51, v53
	ds_bpermute_b32 v52, v218, v50
	ds_bpermute_b32 v53, v219, v51
	s_waitcnt lgkmcnt(1)
	v_add_f32_e32 v50, v50, v52
	s_waitcnt lgkmcnt(0)
	v_add_f32_e32 v51, v51, v53
	ds_bpermute_b32 v52, v219, v50
	ds_bpermute_b32 v53, v220, v51
	s_waitcnt lgkmcnt(1)
	v_add_f32_e32 v50, v50, v52
	s_waitcnt lgkmcnt(0)
	v_add_f32_e32 v51, v51, v53
	ds_bpermute_b32 v52, v220, v50
	ds_bpermute_b32 v53, v221, v51
	s_waitcnt lgkmcnt(1)
	v_add_f32_e32 v50, v50, v52
	s_waitcnt lgkmcnt(0)
	v_add_f32_e32 v51, v51, v53
	ds_bpermute_b32 v52, v221, v50
	ds_bpermute_b32 v53, v222, v51
	s_waitcnt lgkmcnt(1)
	v_add_f32_e32 v52, v50, v52
	s_waitcnt lgkmcnt(0)
	v_add_f32_e32 v50, v51, v53
	v_mov_b32_e32 v51, 0x3727c5ac
	v_fmamk_f32 v50, v50, 0x3a800000, v51
	v_mul_f32_e32 v53, 0x4f800000, v50
	v_cmp_gt_f32_e32 vcc, s11, v50
	ds_bpermute_b32 v54, v222, v52
	s_waitcnt lgkmcnt(0)
	v_add_f32_e32 v54, v52, v54
	v_cndmask_b32_e32 v50, v50, v53, vcc
	v_sqrt_f32_e32 v53, v50
	s_nop 0
	v_add_u32_e32 v55, -1, v53
	v_fma_f32 v56, -v55, v53, v50
	v_cmp_ge_f32_e64 s[4:5], 0, v56
	v_add_u32_e32 v56, 1, v53
	s_nop 0
	v_cndmask_b32_e64 v55, v53, v55, s[4:5]
	v_fma_f32 v53, -v56, v53, v50
	v_cmp_lt_f32_e64 s[4:5], 0, v53
	s_nop 1
	v_cndmask_b32_e64 v53, v55, v56, s[4:5]
	v_mul_f32_e32 v55, 0x37800000, v53
	v_cndmask_b32_e32 v53, v53, v55, vcc
	v_mov_b32_e32 v55, 0x260
	v_cmp_class_f32_e32 vcc, v50, v55
	s_nop 1
	v_cndmask_b32_e32 v50, v53, v50, vcc
	v_div_scale_f32 v53, s[4:5], v50, v50, 1.0
	v_rcp_f32_e32 v56, v53
	s_lshl_b64 s[4:5], s[6:7], 11
	s_add_u32 s6, s8, s4
	s_addc_u32 s7, s9, s5
	v_fma_f32 v57, -v53, v56, 1.0
	v_fmac_f32_e32 v56, v57, v56
	v_div_scale_f32 v57, vcc, 1.0, v50, 1.0
	v_mul_f32_e32 v58, v57, v56
	v_fma_f32 v59, -v53, v58, v57
	v_fmac_f32_e32 v58, v59, v56
	v_fma_f32 v53, -v53, v58, v57
	v_div_fmas_f32 v53, v53, v56, v58
	v_div_fixup_f32 v50, v53, v50, 1.0
	v_pk_mul_f32 v[42:43], v[42:43], v[50:51] op_sel_hi:[1,0]
	v_pk_mul_f32 v[52:53], v[96:97], v[50:51] op_sel_hi:[1,0]
	v_pk_fma_f32 v[42:43], v[26:27], v[42:43], v[30:31]
	v_pk_fma_f32 v[52:53], v[28:29], v[52:53], v[32:33]
	v_cvt_pk_bf16_f32 v42, v42, v43
	s_nop 0
	v_cvt_pk_bf16_f32 v43, v52, v53
	v_lshlrev_b32_e32 v52, 3, v98
	global_store_dwordx2 v52, v[42:43], s[6:7]
	v_pk_mul_f32 v[42:43], v[44:45], v[50:51] op_sel_hi:[1,0]
	v_pk_mul_f32 v[44:45], v[92:93], v[50:51] op_sel_hi:[1,0]
	v_pk_fma_f32 v[42:43], v[18:19], v[42:43], v[22:23]
	v_pk_fma_f32 v[44:45], v[20:21], v[44:45], v[24:25]
	v_cvt_pk_bf16_f32 v42, v42, v43
	s_nop 0
	v_cvt_pk_bf16_f32 v43, v44, v45
	global_store_dwordx2 v52, v[42:43], s[6:7] offset:512
	v_pk_mul_f32 v[42:43], v[46:47], v[50:51] op_sel_hi:[1,0]
	v_pk_mul_f32 v[44:45], v[88:89], v[50:51] op_sel_hi:[1,0]
	v_pk_fma_f32 v[42:43], v[10:11], v[42:43], v[14:15]
	v_pk_fma_f32 v[44:45], v[12:13], v[44:45], v[16:17]
	v_cvt_pk_bf16_f32 v42, v42, v43
	s_nop 0
	v_cvt_pk_bf16_f32 v43, v44, v45
	global_store_dwordx2 v52, v[42:43], s[6:7] offset:1024
	v_pk_mul_f32 v[42:43], v[82:83], v[50:51] op_sel_hi:[1,0]
	v_fmac_f32_e32 v51, 0x3a800000, v54
	v_mul_f32_e32 v44, 0x4f800000, v51
	v_cmp_gt_f32_e32 vcc, s11, v51
	v_pk_fma_f32 v[42:43], v[2:3], v[42:43], v[6:7]
	s_nop 0
	v_cndmask_b32_e32 v46, v51, v44, vcc
	v_sqrt_f32_e32 v47, v46
	v_pk_mul_f32 v[44:45], v[48:49], v[50:51] op_sel_hi:[1,0]
	v_cvt_pk_bf16_f32 v42, v42, v43
	v_add_u32_e32 v48, -1, v47
	v_fma_f32 v49, -v48, v47, v46
	v_cmp_ge_f32_e64 s[4:5], 0, v49
	v_add_u32_e32 v49, 1, v47
	v_pk_fma_f32 v[44:45], v[4:5], v[44:45], v[8:9]
	v_cndmask_b32_e64 v48, v47, v48, s[4:5]
	v_fma_f32 v47, -v49, v47, v46
	v_cmp_lt_f32_e64 s[4:5], 0, v47
	v_cvt_pk_bf16_f32 v43, v44, v45
	global_store_dwordx2 v52, v[42:43], s[6:7] offset:1536
	s_nop 0
	v_cndmask_b32_e64 v47, v48, v49, s[4:5]
	v_mul_f32_e32 v48, 0x37800000, v47
	v_cndmask_b32_e32 v47, v47, v48, vcc
	v_cmp_class_f32_e32 vcc, v46, v55
	s_nop 1
	v_cndmask_b32_e32 v46, v47, v46, vcc
	v_div_scale_f32 v47, s[4:5], v46, v46, 1.0
	v_rcp_f32_e32 v48, v47
	s_or_b32 s4, s1, 31
	s_ashr_i32 s5, s4, 31
	s_lshl_b64 s[4:5], s[4:5], 11
	v_fma_f32 v42, -v47, v48, 1.0
	v_fmac_f32_e32 v48, v42, v48
	v_div_scale_f32 v42, vcc, 1.0, v46, 1.0
	v_mul_f32_e32 v43, v42, v48
	v_fma_f32 v44, -v47, v43, v42
	v_fmac_f32_e32 v43, v44, v48
	v_fma_f32 v42, -v47, v43, v42
	v_div_fmas_f32 v42, v42, v48, v43
	v_div_fixup_f32 v42, v42, v46, 1.0
	v_pk_mul_f32 v[34:35], v[34:35], v[42:43] op_sel_hi:[1,0]
	s_add_u32 s4, s8, s4
	v_pk_mul_f32 v[44:45], v[80:81], v[42:43] op_sel_hi:[1,0]
	v_pk_fma_f32 v[26:27], v[26:27], v[34:35], v[30:31]
	s_addc_u32 s5, s9, s5
	v_pk_fma_f32 v[28:29], v[28:29], v[44:45], v[32:33]
	v_cvt_pk_bf16_f32 v26, v26, v27
	s_movk_i32 s1, 0x3ff
	v_cvt_pk_bf16_f32 v27, v28, v29
	global_store_dwordx2 v52, v[26:27], s[4:5]
	v_pk_mul_f32 v[26:27], v[38:39], v[42:43] op_sel_hi:[1,0]
	v_pk_mul_f32 v[28:29], v[76:77], v[42:43] op_sel_hi:[1,0]
	v_pk_fma_f32 v[18:19], v[18:19], v[26:27], v[22:23]
	v_pk_fma_f32 v[20:21], v[20:21], v[28:29], v[24:25]
	v_cvt_pk_bf16_f32 v18, v18, v19
	s_nop 0
	v_cvt_pk_bf16_f32 v19, v20, v21
	global_store_dwordx2 v52, v[18:19], s[4:5] offset:512
	v_pk_mul_f32 v[18:19], v[40:41], v[42:43] op_sel_hi:[1,0]
	v_pk_mul_f32 v[20:21], v[72:73], v[42:43] op_sel_hi:[1,0]
	v_pk_fma_f32 v[10:11], v[10:11], v[18:19], v[14:15]
	v_pk_fma_f32 v[12:13], v[12:13], v[20:21], v[16:17]
	v_cvt_pk_bf16_f32 v10, v10, v11
	s_nop 0
	v_cvt_pk_bf16_f32 v11, v12, v13
	global_store_dwordx2 v52, v[10:11], s[4:5] offset:1024
	v_pk_mul_f32 v[10:11], v[66:67], v[42:43] op_sel_hi:[1,0]
	v_pk_mul_f32 v[12:13], v[36:37], v[42:43] op_sel_hi:[1,0]
	v_pk_fma_f32 v[2:3], v[2:3], v[10:11], v[6:7]
	v_pk_fma_f32 v[4:5], v[4:5], v[12:13], v[8:9]
	v_cvt_pk_bf16_f32 v2, v2, v3
	s_nop 0
	v_cvt_pk_bf16_f32 v3, v4, v5
	global_store_dwordx2 v52, v[2:3], s[4:5] offset:1536
	v_lshrrev_b32_e32 v2, 20, v0
	v_lshrrev_b32_e32 v0, 10, v0
	v_or_b32_e32 v0, v0, v2
	v_and_or_b32 v0, v0, s1, v189
	v_cmp_eq_u32_e32 vcc, 0, v0
	s_waitcnt vmcnt(0)
	s_barrier
	s_and_saveexec_b64 s[4:5], vcc
	s_cbranch_execz .LBB0_118
	buffer_wbl2 sc1
	s_waitcnt vmcnt(0)
	v_mov_b32_e32 v2, 0x3700
	v_mov_b32_e32 v3, 1
	global_atomic_add v2, v3, s[80:81]
	s_mov_b32 s6, 0
; __global__ void __launch_bounds__(512, 2) fwd_megakernel(Args a) {
;     ...
;     grid.sync();
.Lgsync_spin:
	s_sleep 1
	global_load_dword v4, v2, s[80:81] sc1
	s_add_u32 s6, s6, 1
	s_waitcnt vmcnt(0)
	v_readfirstlane_b32 s7, v4
	s_nop 3
	s_cmp_ge_u32 s7, 0x100
	s_cbranch_scc1 .Lgsync_got
	s_cmp_lt_u32 s6, 0x8000
	s_cbranch_scc1 .Lgsync_spin
.Lgsync_got:
	buffer_inv sc1
	s_waitcnt vmcnt(0)
.LBB0_118:
	s_or_b64 exec, exec, s[4:5]
	v_readlane_b32 s4, v249, 0
	v_readlane_b32 s5, v249, 1
	s_barrier
; __device__ __forceinline__ CArgs* kargs() { CArgs* p = (CArgs*)__builtin_amdgcn_kernarg_segment_ptr(); asm volatile("" : "+s"(p)); return p; }
; #define PHASE_PTRS() CArgs* ka = kargs(); unsigned char* ws = ka->ws; unsigned char* PB = ws + WS_PANEL + (size_t)panel * PANEL_BYTES; \
;         bf16_t* HBp = (bf16_t*)(ws + WS_HB) + (size_t)panel * 256 * DM; float* Hp = ka->out + (size_t)panel * 256 * DM; (void)PB; (void)HBp; (void)Hp
; __global__ void __launch_bounds__(512, 2) fwd_megakernel(Args a) {
;     ...
;     for (int l = 0; l < NLAYER; ++l) {
;         gz_phase(*kargs(), l, panel);
;         {
;             PHASE_PTRS();
;             pg8::Gemm g{HBp, (const bf16_t*)(ws + WS_WIN) + (size_t)l * DINP * DM, DM}; pg8::PanelOrder S{NZ_MAIN / 256};
	s_and_b32 s98, s2, 7
	s_lshr_b32 s99, s2, 5
	s_lshl_b32 s99, s99, 3
	s_or_b32 s98, s98, s99
	s_lshl_b32 s98, s98, 2
	s_add_u32 s98, s98, 0x3600
	v_mov_b32_e32 v2, s98
	global_load_dword v0, v2, s[80:81] sc1
	s_waitcnt vmcnt(0)
	v_readfirstlane_b32 s98, v0
	s_nop 3
	s_lshr_b32 s99, s98, 8
	s_lshl_b32 s100, s98, 24
	s_or_b32 s99, s99, s100
	s_cmp_eq_u32 s99, s98
	s_cselect_b32 s98, 1, 0
	s_nop 0
	v_writelane_b32 v248, s98, 62
	s_load_dword s4, s[4:5], 0x108
	s_mul_i32 s1, s21, s20
	s_lshl_b64 s[88:89], s[2:3], 21
	v_and_b32_e32 v0, 0x70, v1
	v_add_u32_e32 v2, -1, v1
	s_waitcnt lgkmcnt(0)
	s_mul_i32 s1, s1, s4
	s_add_u32 s4, s80, 0x200
	v_writelane_b32 v249, s1, 10
	s_addc_u32 s5, s81, 0
	v_writelane_b32 v249, s4, 11
	v_cmp_lt_i32_e32 vcc, v2, v0
	s_mov_b32 s34, 0x3f317218
	v_writelane_b32 v249, s5, 12
	s_add_u32 s4, s80, 0x1000
	s_addc_u32 s5, s81, 0
	v_writelane_b32 v249, s4, 13
	v_cndmask_b32_e32 v2, v2, v1, vcc
	v_lshlrev_b32_e32 v223, 2, v2
	v_writelane_b32 v249, s5, 14
	s_add_u32 s4, s80, 0x1100
	s_addc_u32 s5, s81, 0
	v_writelane_b32 v249, s4, 15
	v_add_u32_e32 v2, -2, v1
	v_cmp_lt_i32_e32 vcc, v2, v0
	v_writelane_b32 v249, s5, 16
	s_add_u32 s4, s80, 0x1200
	s_addc_u32 s5, s81, 0
	v_writelane_b32 v249, s4, 17
	v_cndmask_b32_e32 v2, v2, v1, vcc
	v_lshlrev_b32_e32 v224, 2, v2
	v_writelane_b32 v249, s5, 18
	s_add_u32 s4, s80, 0x1300
	s_addc_u32 s5, s81, 0
	v_writelane_b32 v249, s4, 19
	s_cmp_eq_u32 s0, 15
	v_add_u32_e32 v2, -4, v1
	v_writelane_b32 v249, s5, 20
	s_cselect_b64 s[4:5], -1, 0
	v_writelane_b32 v249, s4, 21
	s_cmp_eq_u32 s0, 14
	v_cmp_lt_i32_e32 vcc, v2, v0
	v_writelane_b32 v249, s5, 22
	s_cselect_b64 s[4:5], -1, 0
	v_writelane_b32 v249, s4, 23
	s_cmp_eq_u32 s0, 13
	v_cndmask_b32_e32 v2, v2, v1, vcc
	v_writelane_b32 v249, s5, 24
	s_cselect_b64 s[4:5], -1, 0
	v_writelane_b32 v249, s4, 25
	s_cmp_eq_u32 s0, 12
	v_lshlrev_b32_e32 v225, 2, v2
	v_writelane_b32 v249, s5, 26
	s_cselect_b64 s[4:5], -1, 0
	v_writelane_b32 v249, s4, 27
	s_cmp_eq_u32 s0, 11
	v_add_u32_e32 v2, -8, v1
	v_writelane_b32 v249, s5, 28
	s_cselect_b64 s[4:5], -1, 0
	v_writelane_b32 v249, s4, 29
	s_cmp_eq_u32 s0, 10
	v_cmp_lt_i32_e32 vcc, v2, v0
	v_writelane_b32 v249, s5, 30
	s_cselect_b64 s[4:5], -1, 0
	v_writelane_b32 v249, s4, 31
	s_cmp_eq_u32 s0, 9
	v_cndmask_b32_e32 v0, v2, v1, vcc
	v_writelane_b32 v249, s5, 32
	s_cselect_b64 s[4:5], -1, 0
	v_writelane_b32 v249, s4, 33
	s_cmp_eq_u32 s0, 8
	v_mov_b32_e32 v1, 0
	v_writelane_b32 v249, s5, 34
	s_cselect_b64 s[4:5], -1, 0
	v_writelane_b32 v249, s4, 35
	s_cmp_eq_u32 s0, 7
	s_mov_b32 s37, 0
	v_writelane_b32 v249, s5, 36
	s_cselect_b64 s[4:5], -1, 0
	v_writelane_b32 v249, s4, 37
	s_cmp_eq_u32 s0, 6
	v_lshlrev_b32_e32 v226, 2, v0
	v_writelane_b32 v249, s5, 38
	s_cselect_b64 s[4:5], -1, 0
	v_writelane_b32 v249, s4, 39
	s_cmp_eq_u32 s0, 5
	v_mov_b32_e32 v227, 1
	v_writelane_b32 v249, s5, 40
	s_cselect_b64 s[4:5], -1, 0
	v_writelane_b32 v249, s4, 41
	s_cmp_eq_u32 s0, 4
	v_mov_b32_e32 v228, 0x3ecc95a3
	v_writelane_b32 v249, s5, 42
	s_cselect_b64 s[4:5], -1, 0
	v_writelane_b32 v249, s4, 43
	s_cmp_eq_u32 s0, 3
	s_mov_b32 s35, 0x3d800000
	v_writelane_b32 v249, s5, 44
	s_cselect_b64 s[4:5], -1, 0
	v_writelane_b32 v249, s4, 45
	s_cmp_eq_u32 s0, 2
	v_mov_b32_e32 v229, 0x3c088889
	v_writelane_b32 v249, s5, 46
	s_cselect_b64 s[4:5], -1, 0
	v_writelane_b32 v249, s4, 47
	s_cmp_eq_u32 s0, 1
	v_mov_b32_e32 v230, 0x358637bd
	v_writelane_b32 v249, s5, 48
	s_cselect_b64 s[4:5], -1, 0
	v_writelane_b32 v249, s4, 49
	s_cmp_eq_u32 s0, 0
	v_mov_b32_e32 v231, 0x3727c5ac
	v_writelane_b32 v249, s5, 50
	s_cselect_b64 s[4:5], -1, 0
	s_lshl_b32 s0, s0, 8
	s_add_u32 s0, s80, s0
	v_writelane_b32 v249, s4, 51
	s_addc_u32 s1, s81, 0
	v_mov_b32_e32 v232, 0x260
	v_writelane_b32 v249, s5, 52
	s_add_u32 s4, s0, 0x1400
	s_addc_u32 s5, s1, 0
	v_writelane_b32 v249, s4, 53
	s_add_u32 s0, s0, 0x2400
	s_addc_u32 s1, s1, 0
	v_writelane_b32 v249, s5, 54
	v_writelane_b32 v249, s0, 55
	v_mov_b32_e32 v233, 0x1200
	v_mov_b32_e32 v234, 0xe00
	v_writelane_b32 v249, s1, 56
	s_add_u32 s0, s80, 0x3400
	s_addc_u32 s1, s81, 0
	v_writelane_b32 v249, s0, 57
	v_mov_b32_e32 v235, 0x7f800000
	v_mov_b32_e32 v242, v1
	v_writelane_b32 v249, s1, 58
	s_add_u32 s0, s80, 0x3500
	s_addc_u32 s1, s81, 0
	v_writelane_b32 v249, s0, 59
	v_mov_b32_e32 v243, v1
	v_mov_b32_e32 v236, 2
	v_writelane_b32 v249, s1, 60
	s_and_b32 s0, s2, 31
	s_cmp_lg_u32 s0, 0
	s_cselect_b64 s[0:1], -1, 0
	v_writelane_b32 v249, s0, 61
	s_lshl_b64 s[70:71], s[2:3], 17
	s_lshl_b64 s[22:23], s[2:3], 2
	v_writelane_b32 v249, s1, 62
	s_lshl_b64 s[0:1], s[2:3], 16
	v_writelane_b32 v249, s0, 63
	v_mov_b32_e32 v237, 0x400
	s_movk_i32 s90, 0x1400
	v_writelane_b32 v248, s1, 0
	s_lshl_b64 s[0:1], s[2:3], 8
	v_writelane_b32 v248, s0, 1
	s_mov_b32 s91, 0x10000
	s_mov_b32 s86, 0x18000
	v_writelane_b32 v248, s1, 2
	s_lshl_b64 s[0:1], s[2:3], 13
	v_writelane_b32 v248, s0, 3
	s_mov_b32 s87, 0x8000
	s_mov_b32 s33, 0xbfb8aa3b
	v_writelane_b32 v248, s1, 4
	s_lshl_b32 s0, s2, 9
	v_writelane_b32 v248, s0, 5
	s_lshl_b64 s[0:1], s[2:3], 10
	v_writelane_b32 v248, s0, 6
	s_movk_i32 s72, 0x44
	s_movk_i32 s74, 0x220
	v_writelane_b32 v248, s1, 7
	s_lshl_b64 s[0:1], s[2:3], 15
	v_writelane_b32 v248, s0, 8
	s_mov_b32 s93, 0x5040100
	s_mov_b32 s94, 0x7060302
	v_writelane_b32 v248, s1, 9
	s_mul_hi_i32 s0, s2, 0xffff1000
	v_writelane_b32 v248, s0, 10
	s_mul_i32 s0, s2, 0xffff1000
	v_writelane_b32 v248, s0, 11
	s_mul_hi_i32 s0, s2, 0xfffff100
	v_writelane_b32 v248, s0, 12
	s_mul_i32 s0, s2, 0xfffff100
	v_writelane_b32 v248, s0, 13
	v_readlane_b32 s0, v249, 6
	v_readlane_b32 s1, v249, 7
	s_add_u32 s0, s0, 0x6000080
	v_writelane_b32 v248, s0, 14
	s_addc_u32 s0, s1, 0
	v_writelane_b32 v248, s0, 15
	s_add_u32 s0, s88, 0xe140000
	s_addc_u32 s1, s89, 0
	v_writelane_b32 v248, s0, 16
	s_mov_b32 s95, 0xe001000
	s_mov_b32 s96, 0xe003000
	v_writelane_b32 v248, s1, 17
	s_add_u32 s0, s88, 0xe014000
	s_addc_u32 s1, s89, 0
	v_writelane_b32 v248, s0, 18
	s_mov_b32 s97, 0xf800000
	s_mov_b64 s[2:3], -1
	v_writelane_b32 v248, s1, 19
	s_add_u32 s0, s88, 0xe1c0080
	v_writelane_b32 v248, s0, 20
	s_addc_u32 s0, s89, 0
	v_writelane_b32 v248, s0, 21
	s_add_u32 s0, s88, 0xe140080
	v_writelane_b32 v248, s0, 22
	s_addc_u32 s0, s89, 0
	v_writelane_b32 v248, s0, 23
	s_add_u32 s0, s88, 0xe000080
	v_writelane_b32 v248, s0, 24
	s_addc_u32 s0, s89, 0
	v_writelane_b32 v248, s0, 25
	s_add_i32 s0, 0, 0x22000
	v_writelane_b32 v248, s0, 26
	s_add_i32 s0, 0, 0x22004
	v_writelane_b32 v248, s0, 27
	s_add_i32 s1, 0, 0x12800
	v_writelane_b32 v248, s1, 28
	v_writelane_b32 v248, s70, 29
	s_mov_b32 s0, 0xe002000
	s_add_i32 s92, 0, 0x13000
	s_add_i32 s73, 0, 0x12a00
	s_mov_b64 s[8:9], 0
	s_mov_b64 s[6:7], 0x80
	s_mov_b64 s[12:13], 0x14000
	s_mov_b64 s[28:29], 0x800
	s_mov_b64 s[30:31], 0x4000
	s_mov_b64 s[82:83], 0x50000
	s_mov_b64 s[14:15], 0x8000
	s_mov_b64 s[24:25], 0x40000
	s_mov_b64 s[16:17], 0x20000
	s_mov_b32 s18, s37
	v_writelane_b32 v248, s71, 30
	v_writelane_b32 v248, s73, 31
	s_branch .LBB0_120
